# v14: v11 plus removed the unneeded grid barrier between the gating phase and the diff-attention phase
# speedup vs baseline: 1.0059x; 1.0059x over previous
; DI unsigned xb_ld(unsigned* p)              { return __hip_atomic_load(p, __ATOMIC_RELAXED, __HIP_MEMORY_SCOPE_AGENT); }
; DI unsigned xb_add(unsigned* p, unsigned v) { return __hip_atomic_fetch_add(p, v, __ATOMIC_RELAXED, __HIP_MEMORY_SCOPE_AGENT); }
; #define XB_SPIN(cond, bar) do { unsigned _sp = 0; while (cond) { __builtin_amdgcn_s_sleep(1); \
;     if ((++_sp & 255u) == 0u) { if (xb_ld(&(bar)[XB_TMO])) break; if (_sp > XB_SPIN_CAP) { atomicAdd(&(bar)[XB_TMO], 1u); break; } } } } while (0)
; DI bool xb_tid0(int wid) { unsigned m_ = ~0u; int w_ = wid; asm volatile("" : "+s"(m_), "+s"(w_)); return w_ == 0 && __builtin_amdgcn_mbcnt_hi(m_, __builtin_amdgcn_mbcnt_lo(m_, 0u)) == 0u; }
; DI void xcd_barrier(const XcdBarrier& b, int wid) {
;     asm volatile("s_waitcnt vmcnt(0)" ::: "memory");
;     __syncthreads();
;     if (xb_tid0(wid)) {
;         unsigned* bar = b.bar;
;         __builtin_amdgcn_s_waitcnt(0);
;         unsigned nloc = b.st[0], nx = b.st[1];
;         if (nloc == 0u) { xcd_barrier_complete(bar, b.x, nloc, nx); b.st[0] = nloc; b.st[1] = nx; }
;         const unsigned old = xb_add(&bar[XB_XSUB(b.x)], 1u);
;         const unsigned gen = old / nloc;
;         if (old + 1u == (gen + 1u) * nloc) {
;             __builtin_amdgcn_fence(__ATOMIC_RELEASE, "agent");
;             asm volatile("s_waitcnt vmcnt(0)" ::: "memory");
;             const unsigned og = xb_add(&bar[XB_TOP], 1u);
;             const unsigned tg = og / nx;
;             if (og + 1u == (tg + 1u) * nx) xb_add(&bar[XB_TOPGEN], 1u);
;             else XB_SPIN(xb_ld(&bar[XB_TOPGEN]) == tg, bar);
;             __builtin_amdgcn_fence(__ATOMIC_ACQUIRE, "agent");
;             xb_add(&bar[XB_XGEN(b.x)], 1u);
;             asm volatile("s_waitcnt vmcnt(0)" ::: "memory");
;         } else {
;             XB_SPIN(xb_ld(&bar[XB_XGEN(b.x)]) == gen, bar);
;             __builtin_amdgcn_fence(__ATOMIC_ACQUIRE, "agent");
;             asm volatile("s_waitcnt vmcnt(0)" ::: "memory");
;         }
;     }
;     __syncthreads();
; }
.LBB0_2150:
	s_waitcnt vmcnt(0)
	s_mov_b32 s1, s44
	s_mov_b32 s0, -1
	s_barrier
	s_cmp_lg_u32 s1, 0
	v_readlane_b32 s97, v255, 45
	v_readlane_b32 s95, v255, 42
	s_branch .LBB0_2204
